# attention prompt loop: softmax-finish and next-tile global loads moved ahead of the QK block in both halves
# speedup vs baseline: 1.0030x; 1.0030x over previous
.LBB0_701:
	v_add_f32_e32 v150, 0, v146
	v_add_f32_e32 v150, v147, v150
	v_add_f32_e32 v150, v148, v150
	v_add_f32_e32 v150, v149, v150
	v_add_f32_e32 v150, v154, v150
	v_add_f32_e32 v150, v160, v150
	v_add_f32_e32 v150, v161, v150
	v_add_f32_e32 v150, v162, v150
	v_add_f32_e32 v150, v151, v150
	v_add_f32_e32 v150, v152, v150
	v_add_f32_e32 v150, v153, v150
	v_add_f32_e32 v150, v155, v150
	v_exp_f32_e32 v138, v138
	v_add_f32_e32 v150, v156, v150
	v_exp_f32_e32 v139, v139
	v_add_f32_e32 v150, v157, v150
	v_exp_f32_e32 v136, v136
	v_add_f32_e32 v150, v158, v150
	v_exp_f32_e32 v137, v137
	v_add_f32_e32 v150, v159, v150
	v_exp_f32_e32 v134, v134
	v_add_f32_e32 v150, v138, v150
	v_exp_f32_e32 v135, v135
	v_add_f32_e32 v150, v139, v150
	v_exp_f32_e32 v132, v132
	v_add_f32_e32 v150, v136, v150
	v_exp_f32_e32 v133, v133
	v_add_f32_e32 v150, v137, v150
	v_exp_f32_e32 v130, v130
	v_add_f32_e32 v150, v134, v150
	v_exp_f32_e32 v131, v131
	v_add_f32_e32 v150, v135, v150
	v_exp_f32_e32 v144, v144
	v_add_f32_e32 v150, v132, v150
	v_exp_f32_e32 v145, v145
	v_add_f32_e32 v150, v133, v150
	v_exp_f32_e32 v142, v142
	v_add_f32_e32 v150, v130, v150
	v_exp_f32_e32 v143, v143
	v_add_f32_e32 v150, v131, v150
	v_exp_f32_e32 v140, v140
	v_add_f32_e32 v150, v144, v150
	v_exp_f32_e32 v141, v141
	v_add_f32_e32 v150, v145, v150
	v_add_f32_e32 v150, v142, v150
	v_add_f32_e32 v150, v143, v150
	v_add_f32_e32 v150, v140, v150
	v_add_f32_e32 v202, v141, v150
	v_mov_b32_e32 v203, v202
	v_cvt_pk_bf16_f32 v146, v146, v147
	v_cvt_pk_bf16_f32 v147, v148, v149
	v_cvt_pk_bf16_f32 v148, v154, v160
	v_cvt_pk_bf16_f32 v149, v161, v162
	v_cvt_pk_bf16_f32 v154, v151, v152
	v_cvt_pk_bf16_f32 v155, v153, v155
	v_cvt_pk_bf16_f32 v156, v156, v157
	v_cvt_pk_bf16_f32 v157, v158, v159
	v_cvt_pk_bf16_f32 v158, v138, v139
	v_cvt_pk_bf16_f32 v159, v136, v137
	v_cvt_pk_bf16_f32 v160, v134, v135
	v_cvt_pk_bf16_f32 v161, v132, v133
	v_cvt_pk_bf16_f32 v162, v130, v131
	v_cvt_pk_bf16_f32 v163, v144, v145
	v_cvt_pk_bf16_f32 v164, v142, v143
	v_cvt_pk_bf16_f32 v165, v140, v141
	v_permlane32_swap_b32_e32 v202, v203
	v_add_f32_e32 v248, v202, v203
	v_permlane32_swap_b32_e32 v146, v148
	v_permlane32_swap_b32_e32 v147, v149
	v_permlane32_swap_b32_e32 v154, v156
	v_permlane32_swap_b32_e32 v155, v157
	v_permlane32_swap_b32_e32 v158, v160
	v_permlane32_swap_b32_e32 v159, v161
	v_permlane32_swap_b32_e32 v162, v164
	v_permlane32_swap_b32_e32 v163, v165
	v_add_u32_e32 v250, s16, v172
	v_add_u32_e32 v130, 0x80, v250
	v_add_u32_e32 v132, 0xa0, v250
	v_add_u32_e32 v253, s16, v176
	v_ashrrev_i32_e32 v131, 31, v130
	v_ashrrev_i32_e32 v133, 31, v132
	v_add_u32_e32 v150, 0x80, v253
	v_lshlrev_b64 v[138:139], 11, v[130:131]
	v_lshlrev_b32_e32 v251, 1, v174
	v_lshlrev_b64 v[140:141], 11, v[132:133]
	v_ashrrev_i32_e32 v151, 31, v150
	v_or_b32_e32 v138, v138, v251
	v_or_b32_e32 v140, v140, v251
	v_lshlrev_b64 v[150:151], 7, v[150:151]
	v_lshl_add_u64 v[130:131], s[14:15], 0, v[138:139]
	v_lshl_add_u64 v[134:135], s[14:15], 0, v[140:141]
	v_lshl_add_u64 v[138:139], s[64:65], 0, v[138:139]
	v_lshl_add_u64 v[142:143], s[64:65], 0, v[140:141]
	v_lshl_add_u64 v[150:151], v[178:179], 0, v[150:151]
	global_load_dwordx4 v[130:133], v[130:131], off
	s_nop 0
	global_load_dwordx4 v[134:137], v[134:135], off
	s_nop 0
	global_load_dwordx4 v[138:141], v[138:139], off
	s_nop 0
	global_load_dwordx4 v[142:145], v[142:143], off
	s_nop 0
	global_load_dwordx4 v[150:153], v[150:151], off
	s_add_i32 s17, s91, -1
	v_cmp_le_i32_e64 s[10:11], s17, v193
	v_mov_b32_e32 v66, 0xf149f2ca
	v_mov_b32_e32 v67, 0xf149f2ca
	v_mov_b32_e32 v68, 0xf149f2ca
	v_mov_b32_e32 v69, 0xf149f2ca
	v_mov_b32_e32 v70, 0xf149f2ca
	v_mov_b32_e32 v71, 0xf149f2ca
	v_mov_b32_e32 v72, 0xf149f2ca
	v_mov_b32_e32 v73, 0xf149f2ca
	v_mov_b32_e32 v74, 0xf149f2ca
	v_mov_b32_e32 v75, 0xf149f2ca
	v_mov_b32_e32 v76, 0xf149f2ca
	v_mov_b32_e32 v77, 0xf149f2ca
	v_mov_b32_e32 v78, 0xf149f2ca
	v_mov_b32_e32 v79, 0xf149f2ca
	v_mov_b32_e32 v80, 0xf149f2ca
	v_mov_b32_e32 v81, 0xf149f2ca
	v_mov_b32_e32 v82, 0xf149f2ca
	v_mov_b32_e32 v83, 0xf149f2ca
	v_mov_b32_e32 v84, 0xf149f2ca
	v_mov_b32_e32 v85, 0xf149f2ca
	v_mov_b32_e32 v86, 0xf149f2ca
	v_mov_b32_e32 v87, 0xf149f2ca
	v_mov_b32_e32 v88, 0xf149f2ca
	v_mov_b32_e32 v89, 0xf149f2ca
	v_mov_b32_e32 v90, 0xf149f2ca
	v_mov_b32_e32 v91, 0xf149f2ca
	v_mov_b32_e32 v92, 0xf149f2ca
	v_mov_b32_e32 v93, 0xf149f2ca
	v_mov_b32_e32 v94, 0xf149f2ca
	v_mov_b32_e32 v95, 0xf149f2ca
	v_mov_b32_e32 v96, 0xf149f2ca
	v_mov_b32_e32 v97, 0xf149f2ca
	s_and_saveexec_b64 s[12:13], s[10:11]
	s_cbranch_execz .LBB0_703
	ds_read_b128 v[66:69], v185 offset:57344
	ds_read_b128 v[202:205], v185 offset:57472
	s_waitcnt lgkmcnt(1)
	v_mfma_f32_32x32x16_bf16 v[82:97], v[66:69], v[126:129], 0
	ds_read_b128 v[66:69], v198 offset:12288
	ds_read_b128 v[206:209], v198 offset:12416
	ds_read_b128 v[210:213], v186 offset:57344
	ds_read_b128 v[214:217], v185 offset:57600
	s_waitcnt lgkmcnt(3)
	v_mfma_f32_32x32x16_bf16 v[66:81], v[66:69], v[126:129], 0
	s_waitcnt lgkmcnt(1)
	v_mfma_f32_32x32x16_bf16 v[82:97], v[210:213], v[122:125], v[82:97]
	ds_read_b128 v[210:213], v196 offset:12288
	ds_read_b128 v[218:221], v198 offset:12544
	s_waitcnt lgkmcnt(1)
	v_mfma_f32_32x32x16_bf16 v[66:81], v[210:213], v[122:125], v[66:81]
	ds_read_b128 v[210:213], v188 offset:57344
	ds_read_b128 v[222:225], v188 offset:57472
	s_waitcnt lgkmcnt(1)
	v_mfma_f32_32x32x16_bf16 v[82:97], v[210:213], v[118:121], v[82:97]
	ds_read_b128 v[210:213], v197 offset:12288
	ds_read_b128 v[228:231], v197 offset:12416
	s_waitcnt lgkmcnt(1)
	v_mfma_f32_32x32x16_bf16 v[66:81], v[210:213], v[118:121], v[66:81]
	ds_read_b128 v[210:213], v187 offset:57344
	ds_read_b128 v[232:235], v188 offset:57600
	s_waitcnt lgkmcnt(1)
	v_mfma_f32_32x32x16_bf16 v[82:97], v[210:213], v[114:117], v[82:97]
	ds_read_b128 v[210:213], v195 offset:12288
	ds_read_b128 v[236:239], v197 offset:12544
	s_waitcnt lgkmcnt(1)
	v_mfma_f32_32x32x16_bf16 v[66:81], v[210:213], v[114:117], v[66:81]
	v_mfma_f32_32x32x16_bf16 v[82:97], v[202:205], v[110:113], v[82:97]
	v_mfma_f32_32x32x16_bf16 v[66:81], v[206:209], v[110:113], v[66:81]
	ds_read_b128 v[202:205], v186 offset:57472
	ds_read_b128 v[206:209], v186 offset:57600
	s_waitcnt lgkmcnt(1)
	v_mfma_f32_32x32x16_bf16 v[82:97], v[202:205], v[106:109], v[82:97]
	ds_read_b128 v[202:205], v196 offset:12416
	ds_read_b128 v[210:213], v196 offset:12544
	s_waitcnt lgkmcnt(1)
	v_mfma_f32_32x32x16_bf16 v[66:81], v[202:205], v[106:109], v[66:81]
	v_mfma_f32_32x32x16_bf16 v[82:97], v[222:225], v[102:105], v[82:97]
	ds_read_b128 v[202:205], v187 offset:57472
	ds_read_b128 v[222:225], v187 offset:57600
	v_mfma_f32_32x32x16_bf16 v[66:81], v[228:231], v[102:105], v[66:81]
	s_waitcnt lgkmcnt(1)
	v_mfma_f32_32x32x16_bf16 v[82:97], v[202:205], v[98:101], v[82:97]
	ds_read_b128 v[202:205], v195 offset:12416
	ds_read_b128 v[228:231], v195 offset:12544
	s_waitcnt lgkmcnt(1)
	v_mfma_f32_32x32x16_bf16 v[66:81], v[202:205], v[98:101], v[66:81]
	ds_read_b128 v[202:205], v183
	ds_read_b128 v[240:243], v183 offset:32
	s_waitcnt lgkmcnt(1)
	v_mfma_f32_32x32x16_bf16 v[82:97], v[214:217], v[202:205], v[82:97]
	v_mfma_f32_32x32x16_bf16 v[66:81], v[218:221], v[202:205], v[66:81]
	s_waitcnt lgkmcnt(0)
	v_mfma_f32_32x32x16_bf16 v[82:97], v[206:209], v[240:243], v[82:97]
	ds_read_b128 v[202:205], v183 offset:64
	ds_read_b128 v[206:209], v183 offset:96
	v_mfma_f32_32x32x16_bf16 v[66:81], v[210:213], v[240:243], v[66:81]
	s_waitcnt lgkmcnt(1)
	v_mfma_f32_32x32x16_bf16 v[82:97], v[232:235], v[202:205], v[82:97]
	v_mfma_f32_32x32x16_bf16 v[66:81], v[236:239], v[202:205], v[66:81]
	s_waitcnt lgkmcnt(0)
	v_mfma_f32_32x32x16_bf16 v[82:97], v[222:225], v[206:209], v[82:97]
	v_mfma_f32_32x32x16_bf16 v[66:81], v[228:231], v[206:209], v[66:81]
.LBB0_703:
	s_or_b64 exec, exec, s[12:13]
	v_cmp_le_i32_e32 vcc, s17, v200
	s_and_saveexec_b64 s[12:13], vcc
	s_cbranch_execz .LBB0_705
	ds_read_b64_tr_b16 v[208:209], v182 offset:0
	ds_read_b64_tr_b16 v[210:211], v182 offset:0x800
	ds_read_b64_tr_b16 v[212:213], v182 offset:0x1000
	ds_read_b64_tr_b16 v[214:215], v182 offset:0x1800
	ds_read_b64_tr_b16 v[216:217], v182 offset:0x2000
	ds_read_b64_tr_b16 v[218:219], v182 offset:0x2800
	ds_read_b64_tr_b16 v[220:221], v182 offset:0x3000
	ds_read_b64_tr_b16 v[222:223], v182 offset:0x3800
	s_waitcnt lgkmcnt(0)
	s_nop 0
	v_mfma_f32_32x32x16_bf16 v[2:17], v[146:149], v[208:211], v[2:17]
	ds_read_b64_tr_b16 v[208:209], v182 offset:0x200
	ds_read_b64_tr_b16 v[210:211], v182 offset:0xa00
	v_mfma_f32_32x32x16_bf16 v[2:17], v[154:157], v[212:215], v[2:17]
	ds_read_b64_tr_b16 v[212:213], v182 offset:0x1200
	ds_read_b64_tr_b16 v[214:215], v182 offset:0x1a00
	v_mfma_f32_32x32x16_bf16 v[2:17], v[158:161], v[216:219], v[2:17]
	ds_read_b64_tr_b16 v[216:217], v182 offset:0x2200
	ds_read_b64_tr_b16 v[218:219], v182 offset:0x2a00
	ds_read_b64_tr_b16 v[228:229], v182 offset:0x3200
	ds_read_b64_tr_b16 v[230:231], v182 offset:0x3a00
	s_waitcnt lgkmcnt(0)
	v_mfma_f32_32x32x16_bf16 v[2:17], v[162:165], v[220:223], v[2:17]
	v_mfma_f32_32x32x16_bf16 v[50:65], v[146:149], v[208:211], v[50:65]
	ds_read_b64_tr_b16 v[208:209], v182 offset:0x400
	ds_read_b64_tr_b16 v[210:211], v182 offset:0xc00
	v_mfma_f32_32x32x16_bf16 v[50:65], v[154:157], v[212:215], v[50:65]
	ds_read_b64_tr_b16 v[212:213], v182 offset:0x1400
	ds_read_b64_tr_b16 v[214:215], v182 offset:0x1c00
	v_mfma_f32_32x32x16_bf16 v[50:65], v[158:161], v[216:219], v[50:65]
	ds_read_b64_tr_b16 v[216:217], v182 offset:0x2400
	ds_read_b64_tr_b16 v[218:219], v182 offset:0x2c00
	ds_read_b64_tr_b16 v[220:221], v182 offset:0x3400
	ds_read_b64_tr_b16 v[222:223], v182 offset:0x3c00
	s_waitcnt lgkmcnt(0)
	v_mfma_f32_32x32x16_bf16 v[50:65], v[162:165], v[228:231], v[50:65]
	v_mfma_f32_32x32x16_bf16 v[34:49], v[146:149], v[208:211], v[34:49]
	ds_read_b64_tr_b16 v[208:209], v182 offset:0x600
	ds_read_b64_tr_b16 v[210:211], v182 offset:0xe00
	v_mfma_f32_32x32x16_bf16 v[34:49], v[154:157], v[212:215], v[34:49]
	ds_read_b64_tr_b16 v[212:213], v182 offset:0x1600
	ds_read_b64_tr_b16 v[214:215], v182 offset:0x1e00
	v_mfma_f32_32x32x16_bf16 v[34:49], v[158:161], v[216:219], v[34:49]
	ds_read_b64_tr_b16 v[216:217], v182 offset:0x2600
	ds_read_b64_tr_b16 v[218:219], v182 offset:0x2e00
	ds_read_b64_tr_b16 v[228:229], v182 offset:0x3600
	ds_read_b64_tr_b16 v[230:231], v182 offset:0x3e00
	s_waitcnt lgkmcnt(0)
	v_mfma_f32_32x32x16_bf16 v[34:49], v[162:165], v[220:223], v[34:49]
	v_mfma_f32_32x32x16_bf16 v[18:33], v[146:149], v[208:211], v[18:33]
	v_mfma_f32_32x32x16_bf16 v[18:33], v[154:157], v[212:215], v[18:33]
	v_mfma_f32_32x32x16_bf16 v[18:33], v[158:161], v[216:219], v[18:33]
	v_mfma_f32_32x32x16_bf16 v[18:33], v[162:165], v[228:231], v[18:33]
.LBB0_705:
	s_or_b64 exec, exec, s[12:13]
	v_max_f32_e32 v146, v83, v83
	v_max_f32_e32 v147, v82, v82
	v_max_f32_e32 v146, v147, v146
	v_max3_f32 v146, v146, v84, v85
	v_max3_f32 v146, v146, v86, v87
	v_max3_f32 v146, v146, v88, v89
	v_max3_f32 v146, v146, v90, v91
	v_max3_f32 v146, v146, v92, v93
	v_max3_f32 v146, v146, v94, v95
	v_max3_f32 v146, v146, v96, v97
	v_max3_f32 v146, v146, v66, v67
	v_max3_f32 v146, v146, v68, v69
	v_max3_f32 v146, v146, v70, v71
	v_max3_f32 v146, v146, v72, v73
	v_max3_f32 v146, v146, v74, v75
	v_max3_f32 v146, v146, v76, v77
	v_max3_f32 v146, v146, v78, v79
	v_max3_f32 v146, v146, v80, v81
	v_mov_b32_e32 v147, v146
	s_nop 1
	v_permlane32_swap_b32_e32 v146, v147
	v_max_f32_e32 v147, v147, v147
	v_max_f32_e32 v146, v146, v146
	v_max_f32_e32 v146, v146, v147
	v_max_f32_e32 v148, v201, v201
	v_sub_f32_e32 v147, v146, v201
	v_max_f32_e32 v146, v148, v146
	v_sub_f32_e32 v148, v201, v146
	v_mul_f32_e32 v148, 0x3dd53b94, v148
	v_exp_f32_e32 v148, v148
	v_cmp_ge_f32_e32 vcc, s80, v147
	s_cmp_eq_u64 vcc, exec
	s_cselect_b64 s[12:13], -1, 0
	s_barrier
	s_waitcnt vmcnt(0)
	v_cndmask_b32_e64 v254, v148, 1.0, s[12:13]
	v_cmp_gt_f32_e32 vcc, 1.0, v254
	s_waitcnt vmcnt(4)
	ds_write_b128 v189, v[130:133]
	s_waitcnt vmcnt(3)
	ds_write_b128 v190, v[134:137]
	s_waitcnt vmcnt(2)
	ds_write_b128 v191, v[138:141] offset:32768
	s_waitcnt vmcnt(1)
	ds_write_b128 v191, v[142:145] offset:45056
	s_waitcnt vmcnt(0)
	ds_write_b128 v192, v[150:153] offset:32768
	s_cbranch_vccz .LBB0_709
	s_and_saveexec_b64 s[18:19], s[8:9]
	ds_write_b32 v171, v254 offset:128
	s_or_b64 exec, exec, s[18:19]
	s_waitcnt lgkmcnt(0)
	v_add_u32_e32 v142, v167, v170
	ds_read_b128 v[130:133], v142 offset:224
	ds_read_b128 v[134:137], v142 offset:192
	ds_read_b128 v[138:141], v142 offset:160
	ds_read_b128 v[142:145], v142 offset:128
	s_waitcnt lgkmcnt(3)
	v_pk_mul_f32 v[14:15], v[14:15], v[130:131]
	s_waitcnt lgkmcnt(2)
	v_pk_mul_f32 v[10:11], v[10:11], v[134:135]
	s_waitcnt lgkmcnt(1)
	v_pk_mul_f32 v[6:7], v[6:7], v[138:139]
	v_pk_mul_f32 v[16:17], v[16:17], v[132:133]
	v_pk_mul_f32 v[12:13], v[12:13], v[136:137]
	v_pk_mul_f32 v[8:9], v[8:9], v[140:141]
	s_waitcnt lgkmcnt(0)
	v_pk_mul_f32 v[4:5], v[4:5], v[144:145]
	v_pk_mul_f32 v[2:3], v[2:3], v[142:143]
	v_pk_mul_f32 v[62:63], v[62:63], v[130:131]
	v_pk_mul_f32 v[58:59], v[58:59], v[134:135]
	v_pk_mul_f32 v[54:55], v[54:55], v[138:139]
	v_pk_mul_f32 v[64:65], v[64:65], v[132:133]
	v_pk_mul_f32 v[60:61], v[60:61], v[136:137]
	v_pk_mul_f32 v[56:57], v[56:57], v[140:141]
	v_pk_mul_f32 v[52:53], v[52:53], v[144:145]
	v_pk_mul_f32 v[50:51], v[50:51], v[142:143]
	v_pk_mul_f32 v[46:47], v[46:47], v[130:131]
	v_pk_mul_f32 v[42:43], v[42:43], v[134:135]
	v_pk_mul_f32 v[38:39], v[38:39], v[138:139]
	v_pk_mul_f32 v[48:49], v[48:49], v[132:133]
	v_pk_mul_f32 v[44:45], v[44:45], v[136:137]
	v_pk_mul_f32 v[40:41], v[40:41], v[140:141]
	v_pk_mul_f32 v[36:37], v[36:37], v[144:145]
	v_pk_mul_f32 v[34:35], v[34:35], v[142:143]
	v_pk_mul_f32 v[30:31], v[30:31], v[130:131]
	v_pk_mul_f32 v[26:27], v[26:27], v[134:135]
	v_pk_mul_f32 v[22:23], v[22:23], v[138:139]
	v_pk_mul_f32 v[32:33], v[32:33], v[132:133]
	v_pk_mul_f32 v[28:29], v[28:29], v[136:137]
	v_pk_mul_f32 v[24:25], v[24:25], v[140:141]
	v_pk_mul_f32 v[20:21], v[20:21], v[144:145]
	v_pk_mul_f32 v[18:19], v[18:19], v[142:143]
.LBB0_709:
	v_cndmask_b32_e64 v201, v146, v201, s[12:13]
	v_mul_f32_e32 v140, 0xbdd53b94, v201
	v_fmamk_f32 v82, v82, 0x3dd53b94, v140
	v_fmamk_f32 v83, v83, 0x3dd53b94, v140
	v_fmamk_f32 v84, v84, 0x3dd53b94, v140
	v_fmamk_f32 v85, v85, 0x3dd53b94, v140
	v_fmamk_f32 v86, v86, 0x3dd53b94, v140
	v_fmamk_f32 v87, v87, 0x3dd53b94, v140
	v_fmamk_f32 v88, v88, 0x3dd53b94, v140
	v_fmamk_f32 v89, v89, 0x3dd53b94, v140
	v_fmamk_f32 v90, v90, 0x3dd53b94, v140
	v_fmamk_f32 v91, v91, 0x3dd53b94, v140
	v_fmamk_f32 v92, v92, 0x3dd53b94, v140
	v_fmamk_f32 v93, v93, 0x3dd53b94, v140
	v_fmamk_f32 v94, v94, 0x3dd53b94, v140
	v_fmamk_f32 v95, v95, 0x3dd53b94, v140
	v_fmamk_f32 v96, v96, 0x3dd53b94, v140
	v_fmamk_f32 v97, v97, 0x3dd53b94, v140
	v_exp_f32_e32 v133, v82
	v_exp_f32_e32 v136, v83
	v_exp_f32_e32 v137, v84
	v_exp_f32_e32 v141, v85
	v_exp_f32_e32 v142, v86
	v_exp_f32_e32 v144, v87
	v_exp_f32_e32 v145, v88
	v_exp_f32_e32 v146, v89
	v_exp_f32_e32 v130, v90
	v_exp_f32_e32 v131, v91
	v_exp_f32_e32 v132, v92
	v_exp_f32_e32 v134, v93
	v_exp_f32_e32 v135, v94
	v_exp_f32_e32 v138, v95
	v_exp_f32_e32 v139, v96
	v_exp_f32_e32 v143, v97
	v_fmamk_f32 v147, v66, 0x3dd53b94, v140
	v_fmamk_f32 v148, v67, 0x3dd53b94, v140
	v_fmamk_f32 v149, v68, 0x3dd53b94, v140
	v_fmamk_f32 v150, v69, 0x3dd53b94, v140
	v_fmamk_f32 v151, v70, 0x3dd53b94, v140
	v_fmamk_f32 v152, v71, 0x3dd53b94, v140
	v_fmamk_f32 v153, v72, 0x3dd53b94, v140
	v_fmamk_f32 v154, v73, 0x3dd53b94, v140
	v_fmamk_f32 v155, v74, 0x3dd53b94, v140
	v_fmamk_f32 v156, v75, 0x3dd53b94, v140
	v_fmamk_f32 v157, v76, 0x3dd53b94, v140
	v_fmamk_f32 v158, v77, 0x3dd53b94, v140
	v_fmamk_f32 v159, v78, 0x3dd53b94, v140
	v_fmamk_f32 v160, v79, 0x3dd53b94, v140
	v_fmamk_f32 v161, v80, 0x3dd53b94, v140
	v_fmac_f32_e32 v140, 0x3dd53b94, v81
	s_waitcnt lgkmcnt(0)
	s_barrier
	v_exp_f32_e32 v162, v150
	v_add_f32_e32 v150, 0, v133
	v_add_f32_e32 v150, v136, v150
	v_add_f32_e32 v150, v137, v150
	v_add_f32_e32 v150, v141, v150
	v_add_f32_e32 v150, v142, v150
	v_add_f32_e32 v150, v144, v150
	v_add_f32_e32 v150, v145, v150
	v_add_f32_e32 v150, v146, v150
	v_add_f32_e32 v150, v130, v150
	v_add_f32_e32 v150, v131, v150
	v_add_f32_e32 v150, v132, v150
	v_add_f32_e32 v150, v134, v150
	v_exp_f32_e32 v147, v147
	v_add_f32_e32 v150, v135, v150
	v_exp_f32_e32 v148, v148
	v_add_f32_e32 v150, v138, v150
	v_exp_f32_e32 v149, v149
	v_add_f32_e32 v150, v139, v150
	v_add_f32_e32 v150, v143, v150
	v_exp_f32_e32 v163, v151
	v_add_f32_e32 v150, v147, v150
	v_exp_f32_e32 v164, v152
	v_add_f32_e32 v150, v148, v150
	v_exp_f32_e32 v165, v153
	v_add_f32_e32 v150, v149, v150
	v_exp_f32_e32 v210, v154
	v_add_f32_e32 v150, v162, v150
	v_exp_f32_e32 v211, v155
	v_add_f32_e32 v150, v163, v150
	v_exp_f32_e32 v212, v156
	v_add_f32_e32 v150, v164, v150
	v_exp_f32_e32 v213, v157
	v_add_f32_e32 v150, v165, v150
	v_exp_f32_e32 v214, v158
	v_add_f32_e32 v150, v210, v150
	v_exp_f32_e32 v215, v159
	v_add_f32_e32 v150, v211, v150
	v_exp_f32_e32 v216, v160
	v_add_f32_e32 v150, v212, v150
	v_exp_f32_e32 v217, v161
	v_add_f32_e32 v150, v213, v150
	v_exp_f32_e32 v140, v140
	v_add_f32_e32 v150, v214, v150
	v_add_f32_e32 v150, v215, v150
	v_add_f32_e32 v150, v216, v150
	v_add_f32_e32 v150, v217, v150
	v_add_f32_e32 v208, v140, v150
	v_mov_b32_e32 v209, v208
	v_cvt_pk_bf16_f32 v150, v133, v136
	v_cvt_pk_bf16_f32 v151, v137, v141
	v_cvt_pk_bf16_f32 v152, v142, v144
	v_cvt_pk_bf16_f32 v153, v145, v146
	v_cvt_pk_bf16_f32 v154, v130, v131
	v_cvt_pk_bf16_f32 v155, v132, v134
	v_cvt_pk_bf16_f32 v156, v135, v138
	v_cvt_pk_bf16_f32 v157, v139, v143
	v_cvt_pk_bf16_f32 v158, v147, v148
	v_cvt_pk_bf16_f32 v159, v149, v162
	v_cvt_pk_bf16_f32 v160, v163, v164
	v_cvt_pk_bf16_f32 v161, v165, v210
	v_cvt_pk_bf16_f32 v162, v211, v212
	v_cvt_pk_bf16_f32 v163, v213, v214
	v_cvt_pk_bf16_f32 v164, v215, v216
	v_cvt_pk_bf16_f32 v165, v217, v140
	v_permlane32_swap_b32_e32 v208, v209
	v_add_f32_e32 v249, v208, v209
	v_permlane32_swap_b32_e32 v150, v152
	v_permlane32_swap_b32_e32 v151, v153
	v_permlane32_swap_b32_e32 v154, v156
	v_permlane32_swap_b32_e32 v155, v157
	v_permlane32_swap_b32_e32 v158, v160
	v_permlane32_swap_b32_e32 v159, v161
	v_permlane32_swap_b32_e32 v162, v164
	v_permlane32_swap_b32_e32 v163, v165
	v_add_u32_e32 v130, 0xc0, v250
	v_add_u32_e32 v132, 0xe0, v250
	v_ashrrev_i32_e32 v131, 31, v130
	v_ashrrev_i32_e32 v133, 31, v132
	v_add_u32_e32 v146, 0xc0, v253
	v_lshlrev_b64 v[138:139], 11, v[130:131]
	v_lshlrev_b64 v[140:141], 11, v[132:133]
	v_ashrrev_i32_e32 v147, 31, v146
	v_or_b32_e32 v138, v138, v251
	v_or_b32_e32 v140, v140, v251
	v_lshlrev_b64 v[146:147], 7, v[146:147]
	v_lshl_add_u64 v[130:131], s[14:15], 0, v[138:139]
	v_lshl_add_u64 v[134:135], s[14:15], 0, v[140:141]
	v_lshl_add_u64 v[138:139], s[64:65], 0, v[138:139]
	v_lshl_add_u64 v[142:143], s[64:65], 0, v[140:141]
	v_lshl_add_u64 v[146:147], v[178:179], 0, v[146:147]
	global_load_dwordx4 v[130:133], v[130:131], off
	s_nop 0
	global_load_dwordx4 v[134:137], v[134:135], off
	s_nop 0
	global_load_dwordx4 v[138:141], v[138:139], off
	s_nop 0
	global_load_dwordx4 v[142:145], v[142:143], off
	s_nop 0
	global_load_dwordx4 v[146:149], v[146:147], off
	v_cmp_lt_i32_e32 vcc, s17, v193
	v_mov_b32_e32 v66, 0xf149f2ca
	v_mov_b32_e32 v67, 0xf149f2ca
	v_mov_b32_e32 v68, 0xf149f2ca
	v_mov_b32_e32 v69, 0xf149f2ca
	v_mov_b32_e32 v70, 0xf149f2ca
	v_mov_b32_e32 v71, 0xf149f2ca
	v_mov_b32_e32 v72, 0xf149f2ca
	v_mov_b32_e32 v73, 0xf149f2ca
	v_mov_b32_e32 v74, 0xf149f2ca
	v_mov_b32_e32 v75, 0xf149f2ca
	v_mov_b32_e32 v76, 0xf149f2ca
	v_mov_b32_e32 v77, 0xf149f2ca
	v_mov_b32_e32 v78, 0xf149f2ca
	v_mov_b32_e32 v79, 0xf149f2ca
	v_mov_b32_e32 v80, 0xf149f2ca
	v_mov_b32_e32 v81, 0xf149f2ca
	v_mov_b32_e32 v82, 0xf149f2ca
	v_mov_b32_e32 v83, 0xf149f2ca
	v_mov_b32_e32 v84, 0xf149f2ca
	v_mov_b32_e32 v85, 0xf149f2ca
	v_mov_b32_e32 v86, 0xf149f2ca
	v_mov_b32_e32 v87, 0xf149f2ca
	v_mov_b32_e32 v88, 0xf149f2ca
	v_mov_b32_e32 v89, 0xf149f2ca
	v_mov_b32_e32 v90, 0xf149f2ca
	v_mov_b32_e32 v91, 0xf149f2ca
	v_mov_b32_e32 v92, 0xf149f2ca
	v_mov_b32_e32 v93, 0xf149f2ca
	v_mov_b32_e32 v94, 0xf149f2ca
	v_mov_b32_e32 v95, 0xf149f2ca
	v_mov_b32_e32 v96, 0xf149f2ca
	v_mov_b32_e32 v97, 0xf149f2ca
	s_and_saveexec_b64 s[12:13], vcc
	s_cbranch_execz .LBB0_711
	ds_read_b128 v[66:69], v185 offset:32768
	ds_read_b128 v[204:207], v185 offset:32896
	ds_read_b128 v[82:85], v185 offset:45056
	ds_read_b128 v[208:211], v185 offset:33024
	ds_read_b128 v[212:215], v186 offset:32768
	ds_read_b128 v[216:219], v186 offset:32896
	s_waitcnt lgkmcnt(5)
	v_mfma_f32_32x32x16_bf16 v[66:81], v[66:69], v[126:129], 0
	s_waitcnt lgkmcnt(3)
	v_mfma_f32_32x32x16_bf16 v[82:97], v[82:85], v[126:129], 0
	s_waitcnt lgkmcnt(1)
	v_mfma_f32_32x32x16_bf16 v[66:81], v[212:215], v[122:125], v[66:81]
	ds_read_b128 v[212:215], v186 offset:45056
	ds_read_b128 v[220:223], v186 offset:33024
	s_waitcnt lgkmcnt(1)
	v_mfma_f32_32x32x16_bf16 v[82:97], v[212:215], v[122:125], v[82:97]
	ds_read_b128 v[212:215], v188 offset:32768
	ds_read_b128 v[228:231], v188 offset:32896
	s_waitcnt lgkmcnt(1)
	v_mfma_f32_32x32x16_bf16 v[66:81], v[212:215], v[118:121], v[66:81]
	ds_read_b128 v[212:215], v188 offset:45056
	ds_read_b128 v[232:235], v188 offset:33024
	s_waitcnt lgkmcnt(1)
	v_mfma_f32_32x32x16_bf16 v[82:97], v[212:215], v[118:121], v[82:97]
	ds_read_b128 v[212:215], v187 offset:32768
	ds_read_b128 v[236:239], v187 offset:32896
	s_waitcnt lgkmcnt(1)
	v_mfma_f32_32x32x16_bf16 v[66:81], v[212:215], v[114:117], v[66:81]
	ds_read_b128 v[212:215], v187 offset:45056
	ds_read_b128 v[240:243], v187 offset:33024
	s_waitcnt lgkmcnt(1)
	v_mfma_f32_32x32x16_bf16 v[82:97], v[212:215], v[114:117], v[82:97]
	v_mfma_f32_32x32x16_bf16 v[66:81], v[204:207], v[110:113], v[66:81]
	ds_read_b128 v[204:207], v185 offset:45184
	ds_read_b128 v[212:215], v185 offset:45312
	s_waitcnt lgkmcnt(1)
	v_mfma_f32_32x32x16_bf16 v[82:97], v[204:207], v[110:113], v[82:97]
	v_mfma_f32_32x32x16_bf16 v[66:81], v[216:219], v[106:109], v[66:81]
	ds_read_b128 v[204:207], v186 offset:45184
	ds_read_b128 v[216:219], v186 offset:45312
	s_waitcnt lgkmcnt(1)
	v_mfma_f32_32x32x16_bf16 v[82:97], v[204:207], v[106:109], v[82:97]
	v_mfma_f32_32x32x16_bf16 v[66:81], v[228:231], v[102:105], v[66:81]
	ds_read_b128 v[204:207], v188 offset:45184
	ds_read_b128 v[228:231], v188 offset:45312
	s_waitcnt lgkmcnt(1)
	v_mfma_f32_32x32x16_bf16 v[82:97], v[204:207], v[102:105], v[82:97]
	v_mfma_f32_32x32x16_bf16 v[66:81], v[236:239], v[98:101], v[66:81]
	ds_read_b128 v[204:207], v187 offset:45184
	ds_read_b128 v[236:239], v187 offset:45312
	s_waitcnt lgkmcnt(1)
	v_mfma_f32_32x32x16_bf16 v[82:97], v[204:207], v[98:101], v[82:97]
	ds_read_b128 v[204:207], v183
	ds_read_b128 v[244:247], v183 offset:32
	s_waitcnt lgkmcnt(1)
	v_mfma_f32_32x32x16_bf16 v[66:81], v[208:211], v[204:207], v[66:81]
	v_mfma_f32_32x32x16_bf16 v[82:97], v[212:215], v[204:207], v[82:97]
	ds_read_b128 v[204:207], v183 offset:64
	ds_read_b128 v[208:211], v183 offset:96
	s_waitcnt lgkmcnt(2)
	v_mfma_f32_32x32x16_bf16 v[66:81], v[220:223], v[244:247], v[66:81]
	v_mfma_f32_32x32x16_bf16 v[82:97], v[216:219], v[244:247], v[82:97]
	s_waitcnt lgkmcnt(1)
	v_mfma_f32_32x32x16_bf16 v[66:81], v[232:235], v[204:207], v[66:81]
	v_mfma_f32_32x32x16_bf16 v[82:97], v[228:231], v[204:207], v[82:97]
	s_waitcnt lgkmcnt(0)
	v_mfma_f32_32x32x16_bf16 v[66:81], v[240:243], v[208:211], v[66:81]
	v_mfma_f32_32x32x16_bf16 v[82:97], v[236:239], v[208:211], v[82:97]
.LBB0_711:
	s_or_b64 exec, exec, s[12:13]
	s_and_saveexec_b64 s[12:13], s[10:11]
	s_cbranch_execz .LBB0_713
	ds_read_b64_tr_b16 v[210:211], v177 offset:0
	ds_read_b64_tr_b16 v[212:213], v177 offset:0x800
	ds_read_b64_tr_b16 v[214:215], v177 offset:0x1000
	ds_read_b64_tr_b16 v[216:217], v177 offset:0x1800
	ds_read_b64_tr_b16 v[218:219], v177 offset:0x2000
	ds_read_b64_tr_b16 v[220:221], v177 offset:0x2800
	ds_read_b64_tr_b16 v[222:223], v177 offset:0x3000
	ds_read_b64_tr_b16 v[224:225], v177 offset:0x3800
	s_waitcnt lgkmcnt(0)
	s_nop 0
	v_mfma_f32_32x32x16_bf16 v[2:17], v[150:153], v[210:213], v[2:17]
	ds_read_b64_tr_b16 v[210:211], v177 offset:0x200
	ds_read_b64_tr_b16 v[212:213], v177 offset:0xa00
	v_mfma_f32_32x32x16_bf16 v[2:17], v[154:157], v[214:217], v[2:17]
	ds_read_b64_tr_b16 v[214:215], v177 offset:0x1200
	ds_read_b64_tr_b16 v[216:217], v177 offset:0x1a00
	v_mfma_f32_32x32x16_bf16 v[2:17], v[158:161], v[218:221], v[2:17]
	ds_read_b64_tr_b16 v[218:219], v177 offset:0x2200
	ds_read_b64_tr_b16 v[220:221], v177 offset:0x2a00
	ds_read_b64_tr_b16 v[228:229], v177 offset:0x3200
	ds_read_b64_tr_b16 v[230:231], v177 offset:0x3a00
	s_waitcnt lgkmcnt(0)
	v_mfma_f32_32x32x16_bf16 v[2:17], v[162:165], v[222:225], v[2:17]
	v_mfma_f32_32x32x16_bf16 v[50:65], v[150:153], v[210:213], v[50:65]
	ds_read_b64_tr_b16 v[210:211], v177 offset:0x400
	ds_read_b64_tr_b16 v[212:213], v177 offset:0xc00
	v_mfma_f32_32x32x16_bf16 v[50:65], v[154:157], v[214:217], v[50:65]
	ds_read_b64_tr_b16 v[214:215], v177 offset:0x1400
	ds_read_b64_tr_b16 v[216:217], v177 offset:0x1c00
	v_mfma_f32_32x32x16_bf16 v[50:65], v[158:161], v[218:221], v[50:65]
	ds_read_b64_tr_b16 v[218:219], v177 offset:0x2400
	ds_read_b64_tr_b16 v[220:221], v177 offset:0x2c00
	ds_read_b64_tr_b16 v[222:223], v177 offset:0x3400
	ds_read_b64_tr_b16 v[224:225], v177 offset:0x3c00
	s_waitcnt lgkmcnt(0)
	v_mfma_f32_32x32x16_bf16 v[50:65], v[162:165], v[228:231], v[50:65]
	v_mfma_f32_32x32x16_bf16 v[34:49], v[150:153], v[210:213], v[34:49]
	ds_read_b64_tr_b16 v[210:211], v177 offset:0x600
	ds_read_b64_tr_b16 v[212:213], v177 offset:0xe00
	v_mfma_f32_32x32x16_bf16 v[34:49], v[154:157], v[214:217], v[34:49]
	ds_read_b64_tr_b16 v[214:215], v177 offset:0x1600
	ds_read_b64_tr_b16 v[216:217], v177 offset:0x1e00
	v_mfma_f32_32x32x16_bf16 v[34:49], v[158:161], v[218:221], v[34:49]
	ds_read_b64_tr_b16 v[218:219], v177 offset:0x2600
	ds_read_b64_tr_b16 v[220:221], v177 offset:0x2e00
	ds_read_b64_tr_b16 v[228:229], v177 offset:0x3600
	ds_read_b64_tr_b16 v[230:231], v177 offset:0x3e00
	s_waitcnt lgkmcnt(0)
	v_mfma_f32_32x32x16_bf16 v[34:49], v[162:165], v[222:225], v[34:49]
	v_mfma_f32_32x32x16_bf16 v[18:33], v[150:153], v[210:213], v[18:33]
	v_mfma_f32_32x32x16_bf16 v[18:33], v[154:157], v[214:217], v[18:33]
	v_mfma_f32_32x32x16_bf16 v[18:33], v[158:161], v[218:221], v[18:33]
	v_mfma_f32_32x32x16_bf16 v[18:33], v[162:165], v[228:231], v[18:33]

.LBB0_717:
	v_cndmask_b32_e64 v201, v151, v201, s[10:11]
	v_mul_f32_e32 v140, 0xbdd53b94, v201
	v_mov_b32_e32 v141, v140
	v_fmamk_f32 v66, v66, 0x3dd53b94, v140
	v_fmamk_f32 v67, v67, 0x3dd53b94, v140
	v_fmamk_f32 v68, v68, 0x3dd53b94, v140
	v_fmamk_f32 v69, v69, 0x3dd53b94, v140
	v_fmamk_f32 v70, v70, 0x3dd53b94, v140
	v_fmamk_f32 v71, v71, 0x3dd53b94, v140
	v_fmamk_f32 v72, v72, 0x3dd53b94, v140
	v_fmamk_f32 v73, v73, 0x3dd53b94, v140
	v_fmamk_f32 v74, v74, 0x3dd53b94, v140
	v_fmamk_f32 v75, v75, 0x3dd53b94, v140
	v_fmamk_f32 v76, v76, 0x3dd53b94, v140
	v_fmamk_f32 v77, v77, 0x3dd53b94, v140
	v_fmamk_f32 v78, v78, 0x3dd53b94, v140
	v_fmamk_f32 v79, v79, 0x3dd53b94, v140
	v_fmamk_f32 v80, v80, 0x3dd53b94, v140
	v_fmac_f32_e32 v141, 0x3dd53b94, v81
	v_exp_f32_e32 v146, v66
	v_exp_f32_e32 v147, v67
	v_exp_f32_e32 v148, v68
	v_exp_f32_e32 v149, v69
	v_exp_f32_e32 v154, v70
	v_exp_f32_e32 v160, v71
	v_exp_f32_e32 v161, v72
	v_exp_f32_e32 v162, v73
	v_exp_f32_e32 v151, v74
	v_exp_f32_e32 v152, v75
	v_exp_f32_e32 v153, v76
	v_exp_f32_e32 v155, v77
	v_exp_f32_e32 v156, v78
	v_exp_f32_e32 v157, v79
	v_exp_f32_e32 v158, v80
	v_exp_f32_e32 v159, v141
	v_mov_b32_e32 v66, v248
	v_fmac_f32_e32 v66, v199, v173
	v_mov_b32_e32 v173, v249
	s_addk_i32 s16, 0x80
	s_add_i32 s91, s91, 2
	v_pk_fma_f32 v[138:139], v[82:83], s[62:63], v[140:141] op_sel_hi:[1,0,0]
	v_pk_fma_f32 v[136:137], v[84:85], s[62:63], v[140:141] op_sel_hi:[1,0,0]
	v_pk_fma_f32 v[134:135], v[86:87], s[62:63], v[140:141] op_sel_hi:[1,0,0]
	v_pk_fma_f32 v[132:133], v[88:89], s[62:63], v[140:141] op_sel_hi:[1,0,0]
	v_pk_fma_f32 v[130:131], v[90:91], s[62:63], v[140:141] op_sel_hi:[1,0,0]
	v_pk_fma_f32 v[144:145], v[92:93], s[62:63], v[140:141] op_sel_hi:[1,0,0]
	v_pk_fma_f32 v[142:143], v[94:95], s[62:63], v[140:141] op_sel_hi:[1,0,0]
	v_pk_fma_f32 v[140:141], v[96:97], s[62:63], v[140:141] op_sel_hi:[1,0,0]
	v_fmac_f32_e32 v173, v66, v254
	s_cmp_ge_u32 s91, s92
	s_waitcnt lgkmcnt(0)
	s_barrier
	s_cbranch_scc1 .LBB0_719
	v_mov_b32_e32 v199, v150
	s_branch .LBB0_701

	.amdhsa_kernel _Z14fwd_megakernel4Args
		.amdhsa_group_segment_fixed_size 0
		.amdhsa_private_segment_fixed_size 0
		.amdhsa_kernarg_size 504
		.amdhsa_user_sgpr_count 2
		.amdhsa_user_sgpr_dispatch_ptr 0
		.amdhsa_user_sgpr_queue_ptr 0
		.amdhsa_user_sgpr_kernarg_segment_ptr 1
		.amdhsa_user_sgpr_dispatch_id 0
		.amdhsa_user_sgpr_kernarg_preload_length 0
		.amdhsa_user_sgpr_kernarg_preload_offset 0
		.amdhsa_user_sgpr_private_segment_size 0
		.amdhsa_uses_dynamic_stack 0
		.amdhsa_enable_private_segment 0
		.amdhsa_system_sgpr_workgroup_id_x 1
		.amdhsa_system_sgpr_workgroup_id_y 0
		.amdhsa_system_sgpr_workgroup_id_z 0
		.amdhsa_system_sgpr_workgroup_info 0
		.amdhsa_system_vgpr_workitem_id 2
		.amdhsa_next_free_vgpr 256
		.amdhsa_next_free_sgpr 102
		.amdhsa_accum_offset 256
		.amdhsa_reserve_vcc 1
		.amdhsa_float_round_mode_32 0
		.amdhsa_float_round_mode_16_64 0
		.amdhsa_float_denorm_mode_32 3
		.amdhsa_float_denorm_mode_16_64 3
		.amdhsa_dx10_clamp 1
		.amdhsa_ieee_mode 1
		.amdhsa_fp16_overflow 0
		.amdhsa_tg_split 0
		.amdhsa_exception_fp_ieee_invalid_op 0
		.amdhsa_exception_fp_denorm_src 0
		.amdhsa_exception_fp_ieee_div_zero 0
		.amdhsa_exception_fp_ieee_overflow 0
		.amdhsa_exception_fp_ieee_underflow 0
		.amdhsa_exception_fp_ieee_inexact 0
		.amdhsa_exception_int_div_zero 0
	.end_amdhsa_kernel

amdhsa.kernels:
  - .agpr_count:     0
    .args:
      - .offset:         0
        .size:           248
        .value_kind:     by_value
      - .offset:         248
        .size:           4
        .value_kind:     hidden_block_count_x
      - .offset:         252
        .size:           4
        .value_kind:     hidden_block_count_y
      - .offset:         256
        .size:           4
        .value_kind:     hidden_block_count_z
      - .offset:         260
        .size:           2
        .value_kind:     hidden_group_size_x
      - .offset:         262
        .size:           2
        .value_kind:     hidden_group_size_y
      - .offset:         264
        .size:           2
        .value_kind:     hidden_group_size_z
      - .offset:         266
        .size:           2
        .value_kind:     hidden_remainder_x
      - .offset:         268
        .size:           2
        .value_kind:     hidden_remainder_y
      - .offset:         270
        .size:           2
        .value_kind:     hidden_remainder_z
      - .offset:         288
        .size:           8
        .value_kind:     hidden_global_offset_x
      - .offset:         296
        .size:           8
        .value_kind:     hidden_global_offset_y
      - .offset:         304
        .size:           8
        .value_kind:     hidden_global_offset_z
      - .offset:         312
        .size:           2
        .value_kind:     hidden_grid_dims
      - .offset:         336
        .size:           8
        .value_kind:     hidden_multigrid_sync_arg
      - .offset:         368
        .size:           4
        .value_kind:     hidden_dynamic_lds_size
    .group_segment_fixed_size: 0
    .kernarg_segment_align: 8
    .kernarg_segment_size: 504
    .language:       OpenCL C
    .language_version:
      - 2
      - 0
    .max_flat_workgroup_size: 512
    .name:           _Z14fwd_megakernel4Args
    .private_segment_fixed_size: 0
    .sgpr_count:     108
    .sgpr_spill_count: 1
    .symbol:         _Z14fwd_megakernel4Args.kd
    .uniform_work_group_size: 1
    .uses_dynamic_stack: false
    .vgpr_count:     256
    .vgpr_spill_count: 0
    .wavefront_size: 64
